# pp_v16 + RC1 S0c eight lane-masked LDS reads batched (one wait) + S1 tile B-operand reads pipelined two tiles ahead
# speedup vs baseline: 1.0077x; 1.0025x over previous
.Lrc_nopf:
	v_and_b32_e32 v101, 0xffff0000, v42
	v_lshlrev_b32_e32 v100, 16, v42
	v_pk_add_f32 v[194:195], v[194:195], v[196:197] neg_lo:[0,1] neg_hi:[0,1]
	v_lshlrev_b32_e32 v30, 16, v27
	s_waitcnt lgkmcnt(8)
	v_pk_fma_f32 v[70:71], v[194:195], v[70:71], v[196:197]
	v_pk_add_f32 v[194:195], v[100:101], -1.0 op_sel_hi:[1,0]
	s_waitcnt lgkmcnt(5)
	v_mul_f32_e32 v78, v70, v78
	s_waitcnt lgkmcnt(3)
	v_pk_fma_f32 v[74:75], v[194:195], v[74:75], 1.0 op_sel_hi:[1,1,0]
	v_mul_f32_e32 v1, v71, v79
	v_pk_mul_f32 v[70:71], v[70:71], v[74:75]
	v_mul_f32_e32 v79, v1, v1
	v_pk_mul_f32 v[74:75], v[82:83], v[70:71]
	v_fmac_f32_e32 v79, v78, v78
	s_waitcnt lgkmcnt(1)
	v_pk_mul_f32 v[66:67], v[66:67], v[74:75]
	v_and_b32_e32 v75, 0xffff0000, v31
	v_add_f32_e32 v26, 0, v66
	v_add_f32_e32 v42, v67, v26
	v_lshlrev_b32_e32 v74, 16, v31
	v_and_b32_e32 v31, 0xffff0000, v27
	v_and_b32_e32 v27, 0xffff0000, v39
	v_lshlrev_b32_e32 v26, 16, v39
	v_pk_add_f32 v[26:27], v[26:27], v[74:75] neg_lo:[0,1] neg_hi:[0,1]
	v_and_b32_e32 v67, 0xffff0000, v43
	v_pk_fma_f32 v[38:39], v[26:27], v[84:85], v[74:75]
	v_and_b32_e32 v27, 0xffff0000, v35
	v_lshlrev_b32_e32 v26, 16, v35
	v_lshlrev_b32_e32 v66, 16, v43
	v_pk_add_f32 v[26:27], v[26:27], v[30:31] neg_lo:[0,1] neg_hi:[0,1]
	v_and_b32_e32 v43, 0xffff0000, v40
	v_pk_fma_f32 v[26:27], v[26:27], v[72:73], v[30:31]
	v_pk_add_f32 v[30:31], v[66:67], -1.0 op_sel_hi:[1,0]
	v_mul_f32_e32 v73, v26, v80
	v_pk_fma_f32 v[30:31], v[30:31], v[76:77], 1.0 op_sel_hi:[1,1,0]
	v_mul_f32_e32 v72, v27, v81
	v_pk_mul_f32 v[34:35], v[26:27], v[30:31]
	v_and_b32_e32 v31, 0xffff0000, v28
	v_pk_mul_f32 v[26:27], v[38:39], v[34:35]
	v_lshlrev_b32_e32 v30, 16, v28
	v_pk_mul_f32 v[26:27], v[68:69], v[26:27]
	v_and_b32_e32 v69, 0xffff0000, v44
	v_add_f32_e32 v26, v26, v42
	v_add_f32_e32 v74, v27, v26
	v_and_b32_e32 v27, 0xffff0000, v32
	v_lshlrev_b32_e32 v26, 16, v32
	v_lshlrev_b32_e32 v42, 16, v40
	v_pk_add_f32 v[42:43], v[42:43], v[26:27] neg_lo:[0,1] neg_hi:[0,1]
	v_lshlrev_b32_e32 v68, 16, v44
	v_pk_fma_f32 v[54:55], v[42:43], v[54:55], v[26:27]
	v_and_b32_e32 v27, 0xffff0000, v36
	v_lshlrev_b32_e32 v26, 16, v36
	v_pk_add_f32 v[26:27], v[26:27], v[30:31] neg_lo:[0,1] neg_hi:[0,1]
	v_lshlrev_b32_e32 v32, 16, v29
	v_pk_fma_f32 v[26:27], v[26:27], v[50:51], v[30:31]
	v_pk_add_f32 v[30:31], v[68:69], -1.0 op_sel_hi:[1,0]
	v_mul_f32_e32 v44, v26, v46
	v_pk_fma_f32 v[30:31], v[30:31], v[62:63], 1.0 op_sel_hi:[1,1,0]
	v_mul_f32_e32 v40, v27, v47
	v_pk_mul_f32 v[42:43], v[26:27], v[30:31]
	v_lshlrev_b32_e32 v28, 16, v41
	v_pk_mul_f32 v[26:27], v[54:55], v[42:43]
	v_and_b32_e32 v31, 0xffff0000, v45
	s_waitcnt lgkmcnt(0)
	v_pk_mul_f32 v[26:27], v[58:59], v[26:27]
	v_lshlrev_b32_e32 v30, 16, v45
	v_add_f32_e32 v26, v26, v74
	v_add_f32_e32 v36, v27, v26
	v_and_b32_e32 v27, 0xffff0000, v33
	v_lshlrev_b32_e32 v26, 16, v33
	v_and_b32_e32 v33, 0xffff0000, v29
	v_and_b32_e32 v29, 0xffff0000, v41
	v_pk_add_f32 v[28:29], v[28:29], v[26:27] neg_lo:[0,1] neg_hi:[0,1]
	v_fmac_f32_e32 v79, v73, v73
	v_pk_fma_f32 v[26:27], v[28:29], v[56:57], v[26:27]
	v_and_b32_e32 v29, 0xffff0000, v37
	v_lshlrev_b32_e32 v28, 16, v37
	v_pk_add_f32 v[28:29], v[28:29], v[32:33] neg_lo:[0,1] neg_hi:[0,1]
	v_fmac_f32_e32 v79, v72, v72
	v_pk_fma_f32 v[32:33], v[28:29], v[52:53], v[32:33]
	v_pk_add_f32 v[28:29], v[30:31], -1.0 op_sel_hi:[1,0]
	v_mul_f32_e32 v37, v32, v48
	v_pk_fma_f32 v[28:29], v[28:29], v[64:65], 1.0 op_sel_hi:[1,1,0]
	v_fmac_f32_e32 v79, v44, v44
	v_pk_mul_f32 v[28:29], v[32:33], v[28:29]
	v_fmac_f32_e32 v79, v40, v40
	v_pk_mul_f32 v[46:47], v[26:27], v[28:29]
	v_fmac_f32_e32 v79, v37, v37
	v_pk_mul_f32 v[46:47], v[60:61], v[46:47]
	v_lshl_add_u32 v88, v110, 2, s47
	v_add_f32_e32 v32, v46, v36
	v_add_f32_e32 v32, v47, v32
	ds_bpermute_b32 v41, v112, v32
	v_mul_f32_e32 v36, v33, v49
	v_fmac_f32_e32 v79, v36, v36
	ds_bpermute_b32 v33, v112, v79
	v_lshlrev_b32_e32 v58, 16, v18
	s_waitcnt lgkmcnt(1)
	v_add_f32_e32 v32, v32, v41
	ds_bpermute_b32 v45, v113, v32
	ds_read_b32 v41, v88
	ds_read_b128 v[48:51], v167 offset:80
	s_waitcnt lgkmcnt(3)
	v_add_f32_e32 v33, v79, v33
	ds_bpermute_b32 v47, v113, v33
	v_and_b32_e32 v59, 0xffff0000, v18
	s_waitcnt lgkmcnt(3)
	v_add_f32_e32 v32, v32, v45
	ds_bpermute_b32 v52, v114, v32
	v_lshlrev_b32_e32 v18, 16, v19
	s_waitcnt lgkmcnt(1)
	v_add_f32_e32 v53, v33, v47
	v_and_b32_e32 v33, 0xffff0000, v14
	v_and_b32_e32 v19, 0xffff0000, v19
	s_waitcnt lgkmcnt(0)
	v_add_f32_e32 v52, v32, v52
	v_lshlrev_b32_e32 v32, 16, v14
	v_lshlrev_b32_e32 v14, 16, v15
	v_and_b32_e32 v15, 0xffff0000, v15
	v_pk_add_f32 v[58:59], v[58:59], v[32:33] neg_lo:[0,1] neg_hi:[0,1]
	v_pk_add_f32 v[18:19], v[18:19], v[14:15] neg_lo:[0,1] neg_hi:[0,1]
	v_pk_fma_f32 v[32:33], v[58:59], v[22:23], v[32:33]
	v_pk_fma_f32 v[22:23], v[18:19], v[24:25], v[14:15]
	v_lshlrev_b32_e32 v14, 16, v16
	v_and_b32_e32 v15, 0xffff0000, v16
	v_lshlrev_b32_e32 v18, 16, v20
	v_and_b32_e32 v19, 0xffff0000, v20
	v_pk_add_f32 v[18:19], v[18:19], v[14:15] neg_lo:[0,1] neg_hi:[0,1]
	ds_read_b32 v45, v115
	ds_bpermute_b32 v56, v114, v53
	v_pk_fma_f32 v[18:19], v[18:19], v[48:49], v[14:15]
	v_lshlrev_b32_e32 v14, 16, v17
	v_and_b32_e32 v15, 0xffff0000, v17
	v_lshlrev_b32_e32 v16, 16, v21
	v_and_b32_e32 v17, 0xffff0000, v21
	v_pk_add_f32 v[16:17], v[16:17], v[14:15] neg_lo:[0,1] neg_hi:[0,1]
	v_pk_mul_f32 v[58:59], v[32:33], v[52:53] op_sel_hi:[1,0]
	v_pk_fma_f32 v[14:15], v[16:17], v[50:51], v[14:15]
	v_pk_mul_f32 v[24:25], v[22:23], v[52:53] op_sel_hi:[1,0]
	v_pk_mul_f32 v[60:61], v[18:19], v[52:53] op_sel_hi:[1,0]
	v_pk_mul_f32 v[16:17], v[14:15], v[52:53] op_sel_hi:[1,0]
	v_mov_b32_e32 v46, 0
	v_cvt_pk_bf16_f32 v48, v58, v59
	v_cvt_pk_bf16_f32 v49, v24, v25
	v_cvt_pk_bf16_f32 v50, v60, v61
	v_cvt_pk_bf16_f32 v51, v16, v17
	v_mov_b32_e32 v20, 0
	global_store_dwordx4 v[102:103], v[48:51], off
	v_mov_b32_e32 v25, 0
	v_mov_b32_e32 v52, 0
	v_mov_b32_e32 v59, 0
	v_mov_b32_e32 v62, 0
	v_mov_b32_e32 v47, 0
	v_mov_b32_e32 v65, 0
	s_and_saveexec_b64 s[0:1], s[4:5]
	ds_read_b32 v228, v116
	ds_read_b32 v229, v116 offset:4
	ds_read_b32 v230, v116 offset:8
	ds_read_b32 v231, v116 offset:12
	ds_read_b32 v232, v116 offset:16
	ds_read_b32 v233, v116 offset:20
	ds_read_b32 v234, v116 offset:24
	ds_read_b32 v235, v116 offset:28
	s_or_b64 exec, exec, s[0:1]
	ds_read_b32 v16, v115 offset:4
	ds_read_b32 v17, v88 offset:4
	ds_read_b32 v21, v115 offset:8
	ds_read_b32 v24, v88 offset:8
	s_waitcnt lgkmcnt(4)
	s_and_saveexec_b64 s[0:1], s[4:5]
	v_mul_f32_e32 v20, 0x3fb8aa3b, v228
	v_mul_f32_e32 v46, 0x3fb8aa3b, v229
	v_mul_f32_e32 v52, 0x3fb8aa3b, v230
	v_mul_f32_e32 v25, 0x3fb8aa3b, v231
	v_mul_f32_e32 v62, 0x3fb8aa3b, v232
	v_mul_f32_e32 v59, 0x3fb8aa3b, v233
	v_mul_f32_e32 v65, 0x3fb8aa3b, v234
	v_mul_f32_e32 v47, 0x3fb8aa3b, v235
	s_or_b64 exec, exec, s[0:1]
	ds_read_b32 v48, v115 offset:12
	ds_read_b32 v49, v88 offset:12
	ds_read_b32 v57, v115 offset:16
	ds_read_b32 v58, v88 offset:16
	ds_read_b32 v60, v115 offset:20
	ds_read_b32 v61, v88 offset:20
	ds_read_b32 v63, v115 offset:24
	ds_read_b32 v64, v88 offset:24
	ds_read_b32 v50, v115 offset:28
	ds_read_b32 v51, v88 offset:28
	s_waitcnt lgkmcnt(14)
	v_add_f32_e32 v53, v53, v56
	s_mov_b32 s0, 0xf800000
	v_mul_f32_e32 v56, 0x4f800000, v53
	v_cmp_gt_f32_e32 vcc, s0, v53
	v_exp_f32_e32 v65, v65
	v_exp_f32_e32 v62, v62
	v_cndmask_b32_e32 v53, v53, v56, vcc
	v_sqrt_f32_e32 v56, v53
	v_exp_f32_e32 v59, v59
	v_exp_f32_e32 v52, v52
	v_exp_f32_e32 v20, v20
	v_add_u32_e32 v74, -1, v56
	v_fma_f32 v76, -v74, v56, v53
	v_add_u32_e32 v75, 1, v56
	v_cmp_ge_f32_e64 s[0:1], 0, v76
	v_exp_f32_e32 v25, v25
	v_exp_f32_e32 v46, v46
	v_cndmask_b32_e64 v74, v56, v74, s[0:1]
	v_fma_f32 v56, -v75, v56, v53
	v_cmp_lt_f32_e64 s[0:1], 0, v56
	v_exp_f32_e32 v47, v47
	v_sub_f32_e32 v41, v41, v45
	v_cndmask_b32_e64 v56, v74, v75, s[0:1]
	v_mul_f32_e32 v74, 0x37800000, v56
	v_cndmask_b32_e32 v56, v56, v74, vcc
	v_cmp_class_f32_e32 vcc, v53, v168
	v_mul_f32_e32 v41, 0x3fb8aa3b, v41
	v_exp_f32_e32 v41, v41
	v_cndmask_b32_e32 v53, v56, v53, vcc
	v_max_f32_e32 v53, 0x2b8cbccc, v53
	v_div_scale_f32 v56, s[0:1], v53, v53, 1.0
	v_rcp_f32_e32 v74, v56
	s_nop 0
	v_fma_f32 v75, -v56, v74, 1.0
	v_fmac_f32_e32 v74, v75, v74
	v_div_scale_f32 v75, vcc, 1.0, v53, 1.0
	v_mul_f32_e32 v76, v75, v74
	v_fma_f32 v77, -v56, v76, v75
	v_fmac_f32_e32 v76, v77, v74
	v_fma_f32 v56, -v56, v76, v75
	v_div_fmas_f32 v56, v56, v74, v76
	v_div_fixup_f32 v53, v56, v53, 1.0
	s_waitcnt lgkmcnt(3)
	v_mul_f32_e32 v56, 0x3fb8aa3b, v63
	v_mul_f32_e32 v74, 0xbfb8aa3b, v63
	s_waitcnt lgkmcnt(2)
	v_sub_f32_e32 v63, v64, v63
	v_mul_f32_e32 v63, 0x3fb8aa3b, v63
	v_exp_f32_e32 v56, v56
	v_exp_f32_e32 v74, v74
	v_exp_f32_e32 v63, v63
	v_mul_f32_e32 v37, v37, v53
	v_mul_f32_e32 v30, v37, v30
	v_mul_f32_e32 v37, v37, v65
	v_mul_f32_e32 v56, v26, v56
	v_mul_f32_e32 v64, v30, v74
	v_mul_f32_e32 v65, v28, v74
	v_mul_f32_e32 v30, v30, v63
	v_mul_f32_e32 v28, v28, v63
	v_mul_f32_e32 v26, v44, v53
	v_mul_f32_e32 v44, 0x3fb8aa3b, v57
	v_mul_f32_e32 v63, 0xbfb8aa3b, v57
	v_exp_f32_e32 v44, v44
	v_exp_f32_e32 v63, v63
	v_mul_f32_e32 v68, v26, v68
	v_mul_f32_e32 v40, v40, v53
	v_mul_f32_e32 v26, v26, v62
	v_mul_f32_e32 v44, v54, v44
	v_mul_f32_e32 v54, v68, v63
	v_mul_f32_e32 v62, v42, v63
	v_mul_f32_e32 v63, v40, v69
	v_mul_f32_e32 v69, 0x3fb8aa3b, v60
	v_mul_f32_e32 v74, 0xbfb8aa3b, v60
	v_sub_f32_e32 v60, v61, v60
	v_sub_f32_e32 v57, v58, v57
	v_mul_f32_e32 v60, 0x3fb8aa3b, v60
	v_mul_f32_e32 v57, 0x3fb8aa3b, v57
	v_exp_f32_e32 v74, v74
	v_exp_f32_e32 v60, v60
	v_exp_f32_e32 v57, v57
	v_mul_f32_e32 v40, v40, v59
	v_mul_f32_e32 v59, v63, v74
	v_mul_f32_e32 v58, v43, v74
	v_mul_f32_e32 v61, v63, v60
	v_mul_f32_e32 v43, v43, v60
	v_mul_f32_e32 v60, v68, v57
	v_mul_f32_e32 v63, 0x3fb8aa3b, v21
	v_mul_f32_e32 v68, 0xbfb8aa3b, v21
	v_exp_f32_e32 v69, v69
	v_exp_f32_e32 v63, v63
	v_exp_f32_e32 v68, v68
	v_mul_f32_e32 v42, v42, v57
	v_mul_f32_e32 v57, v73, v53
	v_mul_f32_e32 v66, v57, v66
	v_mul_f32_e32 v55, v55, v69
	v_mul_f32_e32 v52, v57, v52
	v_mul_f32_e32 v38, v38, v63
	v_mul_f32_e32 v57, v66, v68
	v_mul_f32_e32 v63, v34, v68
	v_mul_f32_e32 v68, v72, v53
	v_mul_f32_e32 v69, 0x3fb8aa3b, v48
	v_mul_f32_e32 v72, 0xbfb8aa3b, v48
	v_sub_f32_e32 v48, v49, v48
	v_sub_f32_e32 v21, v24, v21
	v_mul_f32_e32 v73, 0x3fb8aa3b, v16
	v_mul_f32_e32 v74, 0xbfb8aa3b, v16
	v_sub_f32_e32 v16, v17, v16
	v_exp_f32_e32 v69, v69
	v_mul_f32_e32 v48, 0x3fb8aa3b, v48
	v_mul_f32_e32 v21, 0x3fb8aa3b, v21
	v_mul_f32_e32 v16, 0x3fb8aa3b, v16
	v_exp_f32_e32 v72, v72
	v_exp_f32_e32 v48, v48
	v_exp_f32_e32 v21, v21
	v_exp_f32_e32 v73, v73
	v_exp_f32_e32 v74, v74
	v_exp_f32_e32 v16, v16
	v_mul_f32_e32 v24, v78, v53
	v_mul_f32_e32 v1, v1, v53
	v_mul_f32_e32 v67, v68, v67
	v_mul_f32_e32 v39, v39, v69
	v_mul_f32_e32 v69, v24, v100
	v_mul_f32_e32 v20, v24, v20
	v_mul_f32_e32 v24, v1, v101
	v_mul_f32_e32 v25, v68, v25
	v_mul_f32_e32 v49, v67, v72
	v_mul_f32_e32 v68, v35, v72
	v_mul_f32_e32 v67, v67, v48
	v_mul_f32_e32 v35, v35, v48
	v_mul_f32_e32 v48, v66, v21
	v_mul_f32_e32 v21, v34, v21
	v_mul_f32_e32 v34, 0x3fb8aa3b, v45
	v_mul_f32_e32 v1, v1, v46
	v_mul_f32_e32 v17, v83, v73
	v_mul_f32_e32 v46, v24, v74
	v_mul_f32_e32 v73, v24, v16
	v_mul_f32_e32 v24, v36, v53
	s_waitcnt lgkmcnt(1)
	v_mul_f32_e32 v36, 0x3fb8aa3b, v50
	v_exp_f32_e32 v34, v34
	v_mul_f32_e32 v66, 0xbfb8aa3b, v45
	v_exp_f32_e32 v36, v36
	v_mul_f32_e32 v53, 0xbfb8aa3b, v50
	v_exp_f32_e32 v66, v66
	v_exp_f32_e32 v53, v53
	v_mul_f32_e32 v47, v24, v47
	v_mul_f32_e32 v34, v82, v34
	v_mul_f32_e32 v31, v24, v31
	v_mul_f32_e32 v36, v27, v36
	v_cvt_pk_bf16_f32 v24, v20, v1
	v_cvt_pk_bf16_f32 v25, v52, v25
	v_cvt_pk_bf16_f32 v26, v26, v40
	v_cvt_pk_bf16_f32 v27, v37, v47
	v_mul_f32_e32 v72, v66, v69
	s_waitcnt lgkmcnt(0)
	v_sub_f32_e32 v50, v51, v50
	v_mul_f32_e32 v51, v31, v53
	ds_write_b128 v169, v[24:27]
	v_cvt_pk_bf16_f32 v24, v34, v17
	v_cvt_pk_bf16_f32 v25, v38, v39
	v_cvt_pk_bf16_f32 v26, v44, v55
	v_cvt_pk_bf16_f32 v27, v56, v36
	v_mul_f32_e32 v66, v70, v66
	v_mul_f32_e32 v45, v71, v74
	v_mul_f32_e32 v69, v41, v69
	v_mul_f32_e32 v53, v29, v53
	ds_write_b128 v169, v[24:27] offset:9216
	v_cvt_pk_bf16_f32 v24, v72, v46
	v_cvt_pk_bf16_f32 v25, v57, v49
	v_cvt_pk_bf16_f32 v26, v54, v59
	v_cvt_pk_bf16_f32 v27, v64, v51
	v_mul_f32_e32 v41, v70, v41
	ds_write_b128 v169, v[24:27] offset:18432
	v_cvt_pk_bf16_f32 v24, v66, v45
	v_cvt_pk_bf16_f32 v25, v63, v68
	v_cvt_pk_bf16_f32 v26, v62, v58
	v_cvt_pk_bf16_f32 v27, v65, v53
	v_cvt_pk_bf16_f32 v1, v69, s0
	v_add_u32_e32 v17, 0, v139
	ds_write_b128 v169, v[24:27] offset:27648
	ds_write_b16 v17, v1 offset:36864
	v_cvt_pk_bf16_f32 v1, v41, s0
	ds_write_b16 v17, v1 offset:46080
	v_cvt_pk_bf16_f32 v1, v32, s0
	v_mul_f32_e32 v16, v71, v16
	ds_write_b16 v17, v1 offset:55296
	v_cvt_pk_bf16_f32 v1, v73, s0
	ds_write_b16 v170, v1 offset:36864
	v_cvt_pk_bf16_f32 v1, v16, s0
	ds_write_b16 v170, v1 offset:46080
	v_cvt_pk_bf16_f32 v1, v33, s0
	ds_write_b16 v170, v1 offset:55296
	v_cvt_pk_bf16_f32 v1, v48, s0
	ds_write_b16 v171, v1 offset:36864
	v_cvt_pk_bf16_f32 v1, v21, s0
	ds_write_b16 v171, v1 offset:46080
	v_cvt_pk_bf16_f32 v1, v22, s0
	ds_write_b16 v171, v1 offset:55296
	v_cvt_pk_bf16_f32 v1, v67, s0
	ds_write_b16 v172, v1 offset:36864
	v_cvt_pk_bf16_f32 v1, v35, s0
	ds_write_b16 v172, v1 offset:46080
	v_cvt_pk_bf16_f32 v1, v23, s0
	ds_write_b16 v172, v1 offset:55296
	v_cvt_pk_bf16_f32 v1, v60, s0
	ds_write_b16 v173, v1 offset:36864
	v_cvt_pk_bf16_f32 v1, v42, s0
	ds_write_b16 v173, v1 offset:46080
	v_cvt_pk_bf16_f32 v1, v18, s0
	v_mul_f32_e32 v50, 0x3fb8aa3b, v50
	ds_write_b16 v173, v1 offset:55296
	v_cvt_pk_bf16_f32 v1, v61, s0
	v_exp_f32_e32 v50, v50
	ds_write_b16 v174, v1 offset:36864
	v_cvt_pk_bf16_f32 v1, v43, s0
	ds_write_b16 v174, v1 offset:46080
	v_cvt_pk_bf16_f32 v1, v19, s0
	ds_write_b16 v174, v1 offset:55296
	v_cvt_pk_bf16_f32 v1, v30, s0
	ds_write_b16 v175, v1 offset:36864
	v_cvt_pk_bf16_f32 v1, v28, s0
	v_mul_f32_e32 v31, v31, v50
	ds_write_b16 v175, v1 offset:46080
	v_cvt_pk_bf16_f32 v1, v14, s0
	v_mul_f32_e32 v29, v29, v50
	ds_write_b16 v175, v1 offset:55296
	v_cvt_pk_bf16_f32 v1, v31, s0
	ds_write_b16 v177, v1 offset:36864
	v_cvt_pk_bf16_f32 v1, v29, s0
	ds_write_b16 v177, v1 offset:46080
	v_cvt_pk_bf16_f32 v1, v15, s0
	ds_write_b16 v177, v1 offset:55296
	s_mov_b64 s[0:1], 0
	v_mov_b32_e32 v1, v161
	v_mov_b32_e32 v14, v160
.LBB0_1070:
	v_add_u32_e32 v14, 0x200, v14
	s_movk_i32 s2, 0x27f
	v_cmp_lt_u32_e32 vcc, s2, v14
	ds_write_b128 v1, v[10:13]
	s_or_b64 s[0:1], vcc, s[0:1]
	v_add_u32_e32 v1, 0x2000, v1
	s_andn2_b64 exec, exec, s[0:1]
	s_cbranch_execnz .LBB0_1070
	s_or_b64 exec, exec, s[0:1]
	v_add_u32_e32 v1, s87, v117
	s_waitcnt lgkmcnt(0)
	s_barrier
	ds_read_b128 v[18:21], v1
	ds_read_b128 v[14:17], v1 offset:64
	ds_read_b128 v[22:25], v148 offset:18432
	ds_read_b128 v[26:29], v148 offset:18496
	ds_read_b128 v[30:33], v190 offset:18432
	ds_read_b128 v[34:37], v190 offset:18496
	s_waitcnt lgkmcnt(3)
	v_mfma_f32_16x16x32_bf16 v[22:25], v[18:21], v[22:25], 0
	s_and_b64 vcc, exec, s[68:69]
	s_waitcnt lgkmcnt(2)
	v_mfma_f32_16x16x32_bf16 v[22:25], v[14:17], v[26:29], v[22:25]
	s_nop 7
	v_cndmask_b32_e64 v1, 0, v22, s[8:9]
	s_cbranch_vccz .LBB0_1073
	ds_write_b32 v178, v1

.LBB0_1079:
	v_cvt_pk_bf16_f32 v1, v1, s0
	v_add_u32_e32 v22, s42, v143
	ds_write_b16 v22, v1
	ds_read_b128 v[22:25], v192 offset:18432
	ds_read_b128 v[26:29], v192 offset:18496
	v_cndmask_b32_e64 v1, 0, 1, s[70:71]
	v_cmp_ne_u32_e64 s[0:1], 1, v1
	s_waitcnt lgkmcnt(6)
	v_mfma_f32_16x16x32_bf16 v[30:33], v[18:21], v[30:33], 0
	s_andn2_b64 vcc, exec, s[70:71]
	s_waitcnt lgkmcnt(6)
	v_mfma_f32_16x16x32_bf16 v[30:33], v[14:17], v[34:37], v[30:33]
	s_nop 7
	v_cndmask_b32_e64 v1, 0, v30, s[16:17]
	s_cbranch_vccnz .LBB0_1081
	ds_write_b32 v191, v1
.LBB0_1081:
	v_cvt_pk_bf16_f32 v1, v1, s0
	v_add_u32_e32 v30, s42, v145
	ds_write_b16 v30, v1
	s_and_b64 vcc, exec, s[0:1]
	v_cndmask_b32_e64 v1, v31, 0, s[18:19]
	s_cbranch_vccnz .LBB0_1083
	ds_write_b32 v187, v1
.LBB0_1083:
	v_cvt_pk_bf16_f32 v1, v1, s0
	v_add_u32_e32 v30, s42, v146
	ds_write_b16 v30, v1
	s_and_b64 vcc, exec, s[0:1]
	v_cndmask_b32_e64 v1, 0, v32, s[20:21]
	s_cbranch_vccnz .LBB0_1085
	ds_write_b32 v188, v1
.LBB0_1085:
	v_cvt_pk_bf16_f32 v1, v1, s0
	v_add_u32_e32 v30, s42, v147
	ds_write_b16 v30, v1
	s_and_b64 vcc, exec, s[0:1]
	v_cndmask_b32_e64 v1, 0, v33, s[22:23]
	s_cbranch_vccnz .LBB0_1087
	ds_write_b32 v189, v1
.LBB0_1087:
	v_cvt_pk_bf16_f32 v1, v1, s0
	v_add_u32_e32 v30, s42, v149
	ds_write_b16 v30, v1
	ds_read_b128 v[30:33], v193 offset:18432
	ds_read_b128 v[34:37], v193 offset:18496
	v_cndmask_b32_e64 v1, 0, 1, s[72:73]
	v_cmp_ne_u32_e64 s[0:1], 1, v1
	s_waitcnt lgkmcnt(6)
	v_mfma_f32_16x16x32_bf16 v[22:25], v[18:21], v[22:25], 0
	s_andn2_b64 vcc, exec, s[72:73]
	s_waitcnt lgkmcnt(6)
	v_mfma_f32_16x16x32_bf16 v[22:25], v[14:17], v[26:29], v[22:25]
	s_nop 7
	v_cndmask_b32_e64 v1, 0, v22, s[24:25]
	s_cbranch_vccnz .LBB0_1089
	ds_write_b32 v191, v1

.LBB0_1095:
	v_cvt_pk_bf16_f32 v1, v1, s0
	v_add_u32_e32 v22, s42, v153
	ds_write_b16 v22, v1
	ds_read_b128 v[22:25], v148 offset:27648
	ds_read_b128 v[26:29], v148 offset:27712
	v_cndmask_b32_e64 v1, 0, 1, s[74:75]
	v_cmp_ne_u32_e64 s[0:1], 1, v1
	s_waitcnt lgkmcnt(6)
	v_mfma_f32_16x16x32_bf16 v[30:33], v[18:21], v[30:33], 0
	s_andn2_b64 vcc, exec, s[74:75]
	s_waitcnt lgkmcnt(6)
	v_mfma_f32_16x16x32_bf16 v[30:33], v[14:17], v[34:37], v[30:33]
	s_nop 7
	v_cndmask_b32_e64 v1, 0, v30, s[34:35]
	s_cbranch_vccnz .LBB0_1097
	ds_write_b32 v191, v1
.LBB0_1097:
	v_cvt_pk_bf16_f32 v1, v1, s0
	v_add_u32_e32 v30, s42, v154
	ds_write_b16 v30, v1
	s_and_b64 vcc, exec, s[0:1]
	v_cndmask_b32_e64 v1, v31, 0, s[36:37]
	s_cbranch_vccnz .LBB0_1099
	ds_write_b32 v187, v1
.LBB0_1099:
	v_cvt_pk_bf16_f32 v1, v1, s0
	v_add_u32_e32 v30, s42, v155
	ds_write_b16 v30, v1
	s_and_b64 vcc, exec, s[0:1]
	v_cndmask_b32_e64 v1, 0, v32, s[38:39]
	s_cbranch_vccnz .LBB0_1101
	ds_write_b32 v188, v1
.LBB0_1101:
	v_cvt_pk_bf16_f32 v1, v1, s0
	v_add_u32_e32 v30, s42, v156
	ds_write_b16 v30, v1
	s_and_b64 vcc, exec, s[0:1]
	v_cndmask_b32_e64 v1, 0, v33, s[40:41]
	s_cbranch_vccnz .LBB0_1103
	ds_write_b32 v189, v1
.LBB0_1103:
	v_cvt_pk_bf16_f32 v1, v1, s0
	v_add_u32_e32 v30, s42, v157
	ds_write_b16 v30, v1
	ds_read_b128 v[30:33], v190 offset:27648
	ds_read_b128 v[34:37], v190 offset:27712
	s_andn2_b64 vcc, exec, s[58:59]
	s_waitcnt lgkmcnt(6)
	v_mfma_f32_16x16x32_bf16 v[22:25], v[18:21], v[22:25], 0
	s_waitcnt lgkmcnt(6)
	v_mfma_f32_16x16x32_bf16 v[22:25], v[14:17], v[26:29], v[22:25]
	s_nop 7
	v_cvt_pk_bf16_f32 v1, v22, s0
	v_cndmask_b32_e64 v1, 0, v1, s[8:9]
	v_add_u32_e32 v22, s43, v140
	ds_write_b16 v22, v1
	v_cvt_pk_bf16_f32 v1, v23, s0
	v_cndmask_b32_e64 v1, v1, 0, s[10:11]
	v_add_u32_e32 v22, s43, v141
	ds_write_b16 v22, v1
	v_cvt_pk_bf16_f32 v1, v24, s0
	v_cndmask_b32_e64 v1, 0, v1, s[12:13]
	v_add_u32_e32 v22, s43, v142
	ds_write_b16 v22, v1
	v_cvt_pk_bf16_f32 v1, v25, s0
	v_cndmask_b32_e64 v1, 0, v1, s[14:15]
	v_add_u32_e32 v22, s43, v143
	ds_write_b16 v22, v1
	ds_read_b128 v[22:25], v192 offset:27648
	ds_read_b128 v[26:29], v192 offset:27712
	s_waitcnt lgkmcnt(6)
	v_mfma_f32_16x16x32_bf16 v[30:33], v[18:21], v[30:33], 0
	s_waitcnt lgkmcnt(6)
	v_mfma_f32_16x16x32_bf16 v[30:33], v[14:17], v[34:37], v[30:33]
	s_nop 7
	v_cvt_pk_bf16_f32 v1, v30, s0
	v_cndmask_b32_e64 v1, 0, v1, s[16:17]
	v_add_u32_e32 v30, s43, v145
	ds_write_b16 v30, v1
	v_cvt_pk_bf16_f32 v1, v31, s0
	v_cndmask_b32_e64 v1, v1, 0, s[18:19]
	v_add_u32_e32 v30, s43, v146
	ds_write_b16 v30, v1
	v_cvt_pk_bf16_f32 v1, v32, s0
	v_cndmask_b32_e64 v1, 0, v1, s[20:21]
	v_add_u32_e32 v30, s43, v147
	ds_write_b16 v30, v1
	v_cvt_pk_bf16_f32 v1, v33, s0
	v_cndmask_b32_e64 v1, 0, v1, s[22:23]
	v_add_u32_e32 v30, s43, v149
	ds_write_b16 v30, v1
	ds_read_b128 v[30:33], v193 offset:27648
	ds_read_b128 v[34:37], v193 offset:27712
	s_waitcnt lgkmcnt(6)
	v_mfma_f32_16x16x32_bf16 v[22:25], v[18:21], v[22:25], 0
	s_waitcnt lgkmcnt(6)
	v_mfma_f32_16x16x32_bf16 v[22:25], v[14:17], v[26:29], v[22:25]
	v_add_u32_e32 v26, v118, v120
	s_nop 6
	v_cvt_pk_bf16_f32 v1, v22, s0
	v_cndmask_b32_e64 v1, 0, v1, s[24:25]
	v_add_u32_e32 v22, s43, v150
	ds_write_b16 v22, v1
	v_cvt_pk_bf16_f32 v1, v23, s0
	v_cndmask_b32_e64 v1, v1, 0, s[26:27]
	v_add_u32_e32 v22, s43, v151
	ds_write_b16 v22, v1
	v_cvt_pk_bf16_f32 v1, v24, s0
	v_cndmask_b32_e64 v1, 0, v1, s[28:29]
	v_add_u32_e32 v22, s43, v152
	ds_write_b16 v22, v1
	v_cvt_pk_bf16_f32 v1, v25, s0
	v_cndmask_b32_e64 v1, 0, v1, s[30:31]
	v_add_u32_e32 v22, s43, v153
	ds_write_b16 v22, v1
	s_waitcnt lgkmcnt(4)
	v_mfma_f32_16x16x32_bf16 v[30:33], v[18:21], v[30:33], 0
	v_mfma_f32_16x16x32_bf16 v[30:33], v[14:17], v[34:37], v[30:33]
	s_nop 7
	v_cvt_pk_bf16_f32 v1, v30, s0
	v_cndmask_b32_e64 v1, 0, v1, s[34:35]
	v_add_u32_e32 v30, s43, v154
	ds_write_b16 v30, v1
	v_cvt_pk_bf16_f32 v1, v31, s0
	v_cndmask_b32_e64 v1, v1, 0, s[36:37]
	v_add_u32_e32 v30, s43, v155
	ds_write_b16 v30, v1
	v_cvt_pk_bf16_f32 v1, v32, s0
	v_cndmask_b32_e64 v1, 0, v1, s[38:39]
	v_add_u32_e32 v30, s43, v156
	ds_write_b16 v30, v1
	v_cvt_pk_bf16_f32 v1, v33, s0
	v_cndmask_b32_e64 v1, 0, v1, s[40:41]
	v_add_u32_e32 v30, s43, v157
	ds_write_b16 v30, v1
	v_add_u32_e32 v1, v118, v106
	s_waitcnt lgkmcnt(0)
	s_barrier
	ds_read_b128 v[14:17], v1 offset:64512
	ds_read_b128 v[18:21], v179 offset:55296
	s_waitcnt lgkmcnt(0)
	v_mfma_f32_16x16x32_bf16 v[14:17], v[14:17], v[18:21], 0
	ds_read_b128 v[18:21], v26 offset:64512
	ds_read_b128 v[22:25], v180 offset:55296
	s_waitcnt lgkmcnt(0)
	v_mfma_f32_16x16x32_bf16 v[14:17], v[18:21], v[22:25], v[14:17]
	s_nop 7
	ds_write2_b32 v181, v14, v15 offset1:65
	ds_write2_b32 v181, v16, v17 offset0:130 offset1:195
	ds_read_b128 v[14:17], v1 offset:64512
	ds_read_b128 v[18:21], v182 offset:55296
	s_waitcnt lgkmcnt(0)
	v_mfma_f32_16x16x32_bf16 v[14:17], v[14:17], v[18:21], 0
	ds_read_b128 v[18:21], v26 offset:64512
	ds_read_b128 v[22:25], v183 offset:55296
	s_waitcnt lgkmcnt(0)
	v_mfma_f32_16x16x32_bf16 v[14:17], v[18:21], v[22:25], v[14:17]
	s_nop 7
	ds_write2_b32 v184, v14, v15 offset1:65
	ds_write2_b32 v184, v16, v17 offset0:130 offset1:195
	s_cbranch_vccnz .LBB0_1107
	v_mov_b32_e32 v60, s97
	ds_read_b128 v[16:19], v60 offset:64
	v_mov_b32_e32 v14, v121
	s_waitcnt lgkmcnt(0)
	ds_read_b128 v[18:21], v60 offset:128
	v_fma_f32 v1, -v16, v14, v122
	s_waitcnt lgkmcnt(0)
	ds_read_b128 v[20:23], v60 offset:192
	v_fma_f32 v15, -v14, v18, v123
	v_fma_f32 v15, -v1, v19, v15
	ds_read_b128 v[24:27], v60 offset:256
	s_waitcnt lgkmcnt(1)
	v_fma_f32 v16, -v14, v20, v124
	v_fma_f32 v16, -v1, v21, v16
	v_fma_f32 v16, -v22, v15, v16
	ds_read_b128 v[18:21], v60 offset:320
	ds_read_b128 v[28:31], v60 offset:336
	s_waitcnt lgkmcnt(2)
	v_fma_f32 v17, -v14, v24, v125
	v_fma_f32 v17, -v1, v25, v17
	v_fma_f32 v17, -v15, v26, v17
	s_waitcnt lgkmcnt(1)
	v_fma_f32 v18, -v14, v18, v126
	v_fma_f32 v18, -v1, v19, v18
	v_fma_f32 v18, -v15, v20, v18
	v_fma_f32 v17, -v16, v27, v17
	v_fma_f32 v18, -v16, v21, v18
	ds_read_b128 v[22:25], v60 offset:384
	s_waitcnt lgkmcnt(1)
	ds_read_b128 v[30:33], v60 offset:400
	v_fma_f32 v18, -v28, v17, v18
	ds_read_b128 v[26:29], v60 offset:448
	s_waitcnt lgkmcnt(1)
	ds_read_b128 v[32:35], v60 offset:464
	v_fma_f32 v19, -v14, v22, v127
	v_fma_f32 v19, -v1, v23, v19
	v_fma_f32 v19, -v15, v24, v19
	s_waitcnt lgkmcnt(1)
	v_fma_f32 v20, -v14, v26, v128
	v_fma_f32 v20, -v1, v27, v20
	v_fma_f32 v20, -v15, v28, v20
	v_fma_f32 v19, -v16, v25, v19
	v_fma_f32 v20, -v16, v29, v20
	v_fma_f32 v19, -v17, v30, v19
	s_waitcnt lgkmcnt(0)
	v_fma_f32 v20, -v17, v32, v20
	v_fma_f32 v19, -v18, v31, v19
	v_fma_f32 v20, -v18, v33, v20
	ds_read_b128 v[22:25], v60 offset:512
	ds_read_b128 v[36:39], v60 offset:528
	v_fma_f32 v20, -v34, v19, v20
	ds_read_b128 v[26:29], v60 offset:576
	ds_read_b128 v[30:33], v60 offset:592
	ds_read_b128 v[40:43], v60 offset:608
	s_waitcnt lgkmcnt(4)
	v_fma_f32 v21, -v14, v22, v129
	v_fma_f32 v21, -v1, v23, v21
	s_waitcnt lgkmcnt(2)
	v_fma_f32 v22, -v14, v26, v130
	v_fma_f32 v22, -v1, v27, v22
	v_fma_f32 v21, -v15, v24, v21
	v_fma_f32 v22, -v15, v28, v22
	v_fma_f32 v21, -v16, v25, v21
	v_fma_f32 v22, -v16, v29, v22
	v_fma_f32 v21, -v17, v36, v21
	s_waitcnt lgkmcnt(1)
	v_fma_f32 v22, -v17, v30, v22
	v_fma_f32 v21, -v18, v37, v21
	v_fma_f32 v22, -v18, v31, v22
	v_fma_f32 v21, -v19, v38, v21
	v_fma_f32 v22, -v19, v32, v22
	v_fma_f32 v21, -v20, v39, v21
	v_fma_f32 v22, -v20, v33, v22
	ds_read_b128 v[34:37], v60 offset:640
	s_waitcnt lgkmcnt(1)
	ds_read_b128 v[42:45], v60 offset:656
	ds_read_b128 v[46:49], v60 offset:672
	v_fma_f32 v22, -v40, v21, v22
	ds_read_b128 v[24:27], v60 offset:704
	ds_read_b128 v[28:31], v60 offset:720
	ds_read_b128 v[38:41], v60 offset:736
	s_waitcnt lgkmcnt(5)
	v_fma_f32 v23, -v14, v34, v131
	v_fma_f32 v23, -v1, v35, v23
	s_waitcnt lgkmcnt(2)
	v_fma_f32 v24, -v14, v24, v132
	v_fma_f32 v24, -v1, v25, v24
	v_fma_f32 v23, -v15, v36, v23
	v_fma_f32 v24, -v15, v26, v24
	v_fma_f32 v23, -v16, v37, v23
	v_fma_f32 v24, -v16, v27, v24
	v_fma_f32 v23, -v17, v42, v23
	s_waitcnt lgkmcnt(1)
	v_fma_f32 v24, -v17, v28, v24
	v_fma_f32 v23, -v18, v43, v23
	v_fma_f32 v24, -v18, v29, v24
	v_fma_f32 v23, -v19, v44, v23
	v_fma_f32 v24, -v19, v30, v24
	v_fma_f32 v23, -v20, v45, v23
	v_fma_f32 v24, -v20, v31, v24
	v_fma_f32 v23, -v21, v46, v23
	s_waitcnt lgkmcnt(0)
	v_fma_f32 v24, -v21, v38, v24
	v_fma_f32 v23, -v22, v47, v23
	v_fma_f32 v24, -v22, v39, v24
	ds_read_b128 v[32:35], v60 offset:768
	ds_read_b128 v[42:45], v60 offset:784
	ds_read_b128 v[46:49], v60 offset:800
	v_fma_f32 v24, -v40, v23, v24
	ds_read_b128 v[26:29], v60 offset:832
	ds_read_b128 v[36:39], v60 offset:848
	ds_read_b128 v[50:53], v60 offset:864
	ds_read_b128 v[54:57], v60 offset:880
	s_waitcnt lgkmcnt(6)
	v_fma_f32 v25, -v14, v32, v133
	s_waitcnt lgkmcnt(3)
	v_fma_f32 v26, -v14, v26, v134
	v_fma_f32 v25, -v1, v33, v25
	v_fma_f32 v26, -v1, v27, v26
	v_fma_f32 v25, -v15, v34, v25
	v_fma_f32 v26, -v15, v28, v26
	v_fma_f32 v25, -v16, v35, v25
	v_fma_f32 v26, -v16, v29, v26
	v_fma_f32 v25, -v17, v42, v25
	s_waitcnt lgkmcnt(2)
	v_fma_f32 v26, -v17, v36, v26
	v_fma_f32 v25, -v18, v43, v25
	v_fma_f32 v26, -v18, v37, v26
	v_fma_f32 v25, -v19, v44, v25
	v_fma_f32 v26, -v19, v38, v26
	v_fma_f32 v25, -v20, v45, v25
	v_fma_f32 v26, -v20, v39, v26
	v_fma_f32 v25, -v21, v46, v25
	s_waitcnt lgkmcnt(1)
	v_fma_f32 v26, -v21, v50, v26
	v_fma_f32 v25, -v22, v47, v25
	v_fma_f32 v26, -v22, v51, v26
	v_fma_f32 v25, -v23, v48, v25
	v_fma_f32 v26, -v23, v52, v26
	v_fma_f32 v25, -v24, v49, v25
	v_fma_f32 v26, -v24, v53, v26
	ds_read_b128 v[30:33], v60 offset:896
	ds_read_b128 v[40:43], v60 offset:912
	ds_read_b128 v[44:47], v60 offset:928
	s_waitcnt lgkmcnt(3)
	ds_read_b128 v[56:59], v60 offset:944
	v_fma_f32 v26, -v54, v25, v26
	ds_read_b128 v[34:37], v60 offset:960
	ds_read_b128 v[48:51], v60 offset:976
	ds_read_b128 v[52:55], v60 offset:992
	s_waitcnt lgkmcnt(3)
	ds_read_b128 v[58:61], v60 offset:1008
	v_fma_f32 v27, -v14, v30, v135
	s_waitcnt lgkmcnt(3)
	v_fma_f32 v28, -v14, v34, v136
	v_fma_f32 v27, -v1, v31, v27
	v_fma_f32 v28, -v1, v35, v28
	v_fma_f32 v27, -v15, v32, v27
	v_fma_f32 v28, -v15, v36, v28
	v_fma_f32 v27, -v16, v33, v27
	v_fma_f32 v28, -v16, v37, v28
	v_fma_f32 v27, -v17, v40, v27
	s_waitcnt lgkmcnt(2)
	v_fma_f32 v28, -v17, v48, v28
	v_fma_f32 v27, -v18, v41, v27
	v_fma_f32 v28, -v18, v49, v28
	v_fma_f32 v27, -v19, v42, v27
	v_fma_f32 v28, -v19, v50, v28
	v_fma_f32 v27, -v20, v43, v27
	v_fma_f32 v28, -v20, v51, v28
	v_fma_f32 v27, -v21, v44, v27
	s_waitcnt lgkmcnt(1)
	v_fma_f32 v28, -v21, v52, v28
	v_fma_f32 v27, -v22, v45, v27
	v_fma_f32 v28, -v22, v53, v28
	v_fma_f32 v27, -v23, v46, v27
	v_fma_f32 v28, -v23, v54, v28
	v_fma_f32 v27, -v24, v47, v27
	v_fma_f32 v28, -v24, v55, v28
	v_fma_f32 v27, -v25, v56, v27
	s_waitcnt lgkmcnt(0)
	v_fma_f32 v28, -v25, v58, v28
	v_fma_f32 v27, -v26, v57, v27
	v_fma_f32 v28, -v26, v59, v28
	s_nop 0
	v_fma_f32 v28, -v60, v27, v28
	s_and_saveexec_b64 s[0:1], s[6:7]
	s_cbranch_execz .LBB0_1106
	v_readlane_b32 s2, v238, 39
	v_cvt_pk_bf16_f32 v14, v14, s0
	v_cvt_pk_bf16_f32 v1, v1, s0
	v_add_u32_e32 v29, s2, v158
	v_readlane_b32 s2, v238, 43
	ds_write_b16 v29, v14
	s_nop 0
	v_add_u32_e32 v14, s2, v158
	v_readlane_b32 s2, v238, 49
	ds_write_b16 v14, v1
	v_cvt_pk_bf16_f32 v1, v15, s0
	v_add_u32_e32 v14, s2, v158
	v_readlane_b32 s2, v238, 50
	ds_write_b16 v14, v1
	v_cvt_pk_bf16_f32 v1, v16, s0
	v_add_u32_e32 v14, s2, v158
	v_readlane_b32 s2, v238, 51
	ds_write_b16 v14, v1
	v_cvt_pk_bf16_f32 v1, v17, s0
	v_add_u32_e32 v14, s2, v158
	v_readlane_b32 s2, v238, 52
	ds_write_b16 v14, v1
	v_cvt_pk_bf16_f32 v1, v18, s0
	v_add_u32_e32 v14, s2, v158
	v_readlane_b32 s2, v238, 53
	ds_write_b16 v14, v1
	v_cvt_pk_bf16_f32 v1, v19, s0
	v_add_u32_e32 v14, s2, v158
	v_readlane_b32 s2, v238, 54
	ds_write_b16 v14, v1
	v_cvt_pk_bf16_f32 v1, v20, s0
	v_add_u32_e32 v14, s2, v158
	v_readlane_b32 s2, v238, 55
	ds_write_b16 v14, v1
	v_cvt_pk_bf16_f32 v1, v21, s0
	v_add_u32_e32 v14, s2, v158
	v_readlane_b32 s2, v238, 56
	ds_write_b16 v14, v1
	v_cvt_pk_bf16_f32 v1, v22, s0
	v_add_u32_e32 v14, s2, v158
	v_readlane_b32 s2, v238, 57
	ds_write_b16 v14, v1
	v_cvt_pk_bf16_f32 v1, v23, s0
	v_add_u32_e32 v14, s2, v158
	ds_write_b16 v14, v1
	v_cvt_pk_bf16_f32 v1, v24, s0
	v_add_u32_e32 v14, s92, v158
	ds_write_b16 v14, v1
	v_cvt_pk_bf16_f32 v1, v25, s0
	v_add_u32_e32 v14, s86, v158
	ds_write_b16 v14, v1
	v_cvt_pk_bf16_f32 v1, v26, s0
	v_add_u32_e32 v14, s33, v158
	ds_write_b16 v14, v1
	v_cvt_pk_bf16_f32 v1, v27, s0
	v_add_u32_e32 v14, s50, v158
	ds_write_b16 v14, v1
	v_cvt_pk_bf16_f32 v1, v28, s0
	v_add_u32_e32 v14, s51, v158
	ds_write_b16 v14, v1
